# v13 plus nt hint on write-once stores: f32 K/V window outputs (in-proj epilogue) and y outputs (out-proj epilogue)
# baseline (speedup 1.0000x reference)
; #define LAS __attribute__((address_space(3)))
; #define NTLD(p) __builtin_nontemporal_load(p)
;     __device__ __forceinline__ void operator()(const f32x4 (&acc)[2][2][4][2], const pg8::Unit& u, int wr, int wc, int fr, int fq) const {
;     ...
;         const int pm = u.pm; const bool sample = pm >= (MP / 256);
;         const bf16* xb = xbf + (size_t)pm * 256 * DM;
;         float* ob = sample ? out + OUT_YS + (size_t)(pm - MP / 256) * 256 * DM : out + OUT_YP + (size_t)pm * 256 * DM;
;         LAS unsigned char* T = stg + (wr * 4 + wc) * 2048;
;         const int lane = fr + 16 * fq, rr = lane >> 3, p = lane & 7;
;         const int woff0 = fr * 128 + ((fq ^ (fr & 7)) << 4), woff1 = fr * 128 + (((4 + fq) ^ (fr & 7)) << 4);
;         const int roff = rr * 128 + ((p ^ rr) << 4);
;         const int cb = 256 * u.pn + 32 * wc + 4 * p;
; #pragma unroll
;         for (int ai = 0; ai < 2; ++ai) {
;             v4u xv[4][2][2];
; #pragma unroll
;             for (int m = 0; m < 4; ++m) {
;                 const size_t ro = (size_t)(128 * ai + 64 * wr + 16 * m + rr) * DM + (cb & ~7);
; #pragma unroll
;                 for (int bj = 0; bj < 2; ++bj) { xv[m][bj][0] = NTLD((const v4u*)(xb + ro + 128 * bj)); xv[m][bj][1] = NTLD((const v4u*)(xb + ro + 8 * DM + 128 * bj)); }
;             }
; #pragma unroll
;             for (int m = 0; m < 4; ++m) {
;                 const size_t ro = (size_t)(128 * ai + 64 * wr + 16 * m + rr) * DM + cb;
; #pragma unroll
;                 for (int bj = 0; bj < 2; ++bj) {
;                     *(LAS f32x4*)(T + woff0) = acc[ai][bj][m][0]; *(LAS f32x4*)(T + woff1) = acc[ai][bj][m][1];
;                     const f32x4 a0 = *(const LAS f32x4*)(T + roff), a1 = *(const LAS f32x4*)(T + roff + 1024);
;                     const v4u t0 = xv[m][bj][0], t1 = xv[m][bj][1];
;                     const unsigned u0 = (p & 1) ? t0.z : t0.x, u1 = (p & 1) ? t0.w : t0.y, u2 = (p & 1) ? t1.z : t1.x, u3 = (p & 1) ? t1.w : t1.y;
;                     *(f32x4*)(ob + ro + 128 * bj) = (f32x4){bflo(u0), bfhi(u0), bflo(u1), bfhi(u1)} + a0; *(f32x4*)(ob + ro + 8 * DM + 128 * bj) = (f32x4){bflo(u2), bfhi(u2), bflo(u3), bfhi(u3)} + a1;
.LBB0_1239:
	s_add_i32 s6, s4, 0xffffff00
	s_ashr_i32 s5, s4, 31
	s_lshl_b64 s[22:23], s[6:7], 20
	s_add_u32 s6, s49, s22
	s_addc_u32 s15, s50, s23
	s_lshl_b64 s[22:23], s[4:5], 20
	s_add_u32 s17, s56, s22
	s_addc_u32 s22, s57, s23
	s_cmpk_gt_i32 s4, 0xff
	s_cselect_b32 s15, s15, s22
	s_cselect_b32 s6, s6, s17
	s_lshl_b64 s[4:5], s[4:5], 19
	v_mov_b32_e32 v134, v172
	v_mov_b32_e32 v135, v173
	s_add_u32 s4, s41, s4
	s_addc_u32 s5, s42, s5
	v_lshl_add_u32 v128, v135, 4, v134
	s_lshl_b32 s17, s58, 8
	v_ashrrev_i32_e32 v136, 3, v128
	v_and_b32_e32 v128, 7, v134
	s_or_b32 s17, s17, s44
	v_lshlrev_b32_e32 v137, 2, v128
	v_mov_b32_e32 v128, s17
	v_add_u32_e32 v166, s43, v136
	v_bitop3_b32 v128, v137, s54, v128 bitop3:0xc8
	v_ashrrev_i32_e32 v129, 31, v128
	v_ashrrev_i32_e32 v167, 31, v166
	v_lshl_add_u64 v[168:169], v[128:129], 1, s[4:5]
	v_lshlrev_b64 v[128:129], 11, v[166:167]
	v_lshl_add_u64 v[128:129], v[168:169], 0, v[128:129]
	global_load_dwordx4 v[182:185], v[128:129], off nt
	global_load_dwordx4 v[190:193], v[128:129], off offset:256 nt
	v_add_co_u32_e32 v130, vcc, s40, v128
	v_or_b32_e32 v128, s17, v137
	s_nop 0
	v_addc_co_u32_e32 v131, vcc, 0, v129, vcc
	global_load_dwordx4 v[186:189], v[130:131], off nt
	global_load_dwordx4 v[194:197], v[130:131], off offset:256 nt
	v_add_u32_e32 v222, 16, v166
	v_mov_b32_e32 v132, s6
	v_mov_b32_e32 v133, s15
	v_ashrrev_i32_e32 v129, 31, v128
	v_ashrrev_i32_e32 v223, 31, v222
	v_bitop3_b32 v138, v134, v135, 7 bitop3:0x6c
	v_add_u32_e32 v135, 4, v135
	v_lshl_add_u64 v[164:165], v[128:129], 2, v[132:133]
	v_lshlrev_b64 v[128:129], 11, v[222:223]
	v_bitop3_b32 v135, v135, v134, 7 bitop3:0x78
	v_lshl_add_u32 v130, v134, 7, s51
	v_lshl_add_u64 v[128:129], v[168:169], 0, v[128:129]
	v_lshl_add_u32 v179, v138, 4, v130
	v_lshl_add_u32 v180, v135, 4, v130
	v_add_co_u32_e32 v130, vcc, s40, v128
	v_add_u32_e32 v224, 32, v166
	s_nop 0
	v_addc_co_u32_e32 v131, vcc, 0, v129, vcc
	global_load_dwordx4 v[198:201], v[128:129], off nt
	global_load_dwordx4 v[202:205], v[128:129], off offset:256 nt
	global_load_dwordx4 v[206:209], v[130:131], off nt
	global_load_dwordx4 v[210:213], v[130:131], off offset:256 nt
	v_ashrrev_i32_e32 v225, 31, v224
	v_lshlrev_b64 v[128:129], 11, v[224:225]
	v_lshl_add_u64 v[128:129], v[168:169], 0, v[128:129]
	v_add_co_u32_e32 v130, vcc, s40, v128
	v_add_u32_e32 v170, 48, v166
	s_nop 0
	v_addc_co_u32_e32 v131, vcc, 0, v129, vcc
	global_load_dwordx4 v[214:217], v[128:129], off nt
	global_load_dwordx4 v[144:147], v[128:129], off offset:256 nt
	global_load_dwordx4 v[218:221], v[130:131], off nt
	global_load_dwordx4 v[148:151], v[130:131], off offset:256 nt
	v_ashrrev_i32_e32 v171, 31, v170
	v_lshlrev_b64 v[128:129], 11, v[170:171]
	v_lshl_add_u64 v[128:129], v[168:169], 0, v[128:129]
	v_lshlrev_b32_e32 v139, 7, v136
	v_bitop3_b32 v136, v136, v134, 7 bitop3:0x78
	v_add_co_u32_e32 v132, vcc, s40, v128
	v_lshlrev_b32_e32 v136, 4, v136
	s_nop 0
	v_addc_co_u32_e32 v133, vcc, 0, v129, vcc
	v_add3_u32 v178, s51, v139, v136
	v_and_b32_e32 v181, 1, v134
	global_load_dwordx4 v[136:139], v[128:129], off nt
	s_nop 0
	global_load_dwordx4 v[128:131], v[128:129], off offset:256 nt
	s_nop 0
	global_load_dwordx4 v[140:143], v[132:133], off nt
	s_nop 0
	global_load_dwordx4 v[132:135], v[132:133], off offset:256 nt
	ds_write_b128 v179, v[124:127]
	ds_write_b128 v180, v[120:123]
	ds_read_b128 v[120:123], v178
	ds_read_b128 v[124:127], v178 offset:1024
	v_cmp_eq_u32_e32 vcc, 0, v181
	v_lshlrev_b64 v[226:227], 12, v[166:167]
	v_lshl_add_u64 v[226:227], v[164:165], 0, v[226:227]
	s_waitcnt vmcnt(0)
	v_cndmask_b32_e32 v167, v184, v182, vcc
	v_cndmask_b32_e32 v181, v185, v183, vcc
	v_lshlrev_b32_e32 v182, 16, v167
	v_and_b32_e32 v183, 0xffff0000, v167
	v_lshlrev_b32_e32 v184, 16, v181
	v_and_b32_e32 v185, 0xffff0000, v181
	s_waitcnt lgkmcnt(1)
	v_pk_add_f32 v[120:121], v[120:121], v[182:183]
	v_cndmask_b32_e32 v186, v188, v186, vcc
	v_pk_add_f32 v[122:123], v[122:123], v[184:185]
	v_cndmask_b32_e32 v187, v189, v187, vcc
	global_store_dwordx4 v[226:227], v[120:123], off nt
	s_nop 1
	v_lshlrev_b32_e32 v120, 16, v186
	v_and_b32_e32 v121, 0xffff0000, v186
	v_lshlrev_b32_e32 v122, 16, v187
	v_and_b32_e32 v123, 0xffff0000, v187
	s_waitcnt lgkmcnt(0)
	v_pk_add_f32 v[120:121], v[124:125], v[120:121]
	v_add_co_u32_e64 v124, s[4:5], s47, v226
	v_pk_add_f32 v[122:123], v[126:127], v[122:123]
	s_nop 0
	v_addc_co_u32_e64 v125, s[4:5], 0, v227, s[4:5]
	global_store_dwordx4 v[124:125], v[120:123], off nt
	ds_write_b128 v179, v[116:119]
	ds_write_b128 v180, v[112:115]
	ds_read_b128 v[112:115], v178
	ds_read_b128 v[116:119], v178 offset:1024
	v_cndmask_b32_e32 v121, v192, v190, vcc
	v_cndmask_b32_e32 v123, v193, v191, vcc
	v_lshlrev_b32_e32 v120, 16, v121
	v_and_b32_e32 v121, 0xffff0000, v121
	v_lshlrev_b32_e32 v122, 16, v123
	v_and_b32_e32 v123, 0xffff0000, v123
	v_cndmask_b32_e32 v126, v196, v194, vcc
	v_cndmask_b32_e32 v127, v197, v195, vcc
	s_waitcnt lgkmcnt(1)
	v_pk_add_f32 v[112:113], v[112:113], v[120:121]
	v_pk_add_f32 v[114:115], v[114:115], v[122:123]
	global_store_dwordx4 v[226:227], v[112:115], off offset:512 nt
	s_nop 1
	v_lshlrev_b32_e32 v112, 16, v126
	v_and_b32_e32 v113, 0xffff0000, v126
	v_lshlrev_b32_e32 v114, 16, v127
	v_and_b32_e32 v115, 0xffff0000, v127
	s_waitcnt lgkmcnt(0)
	v_pk_add_f32 v[112:113], v[116:117], v[112:113]
	v_pk_add_f32 v[114:115], v[118:119], v[114:115]
	global_store_dwordx4 v[124:125], v[112:115], off offset:512 nt
	ds_write_b128 v179, v[108:111]
	ds_write_b128 v180, v[104:107]
	ds_read_b128 v[104:107], v178
	ds_read_b128 v[108:111], v178 offset:1024
	v_cndmask_b32_e32 v115, v200, v198, vcc
	v_cndmask_b32_e32 v117, v201, v199, vcc
	v_lshlrev_b64 v[112:113], 12, v[222:223]
	v_lshlrev_b32_e32 v114, 16, v115
	v_and_b32_e32 v115, 0xffff0000, v115
	v_lshlrev_b32_e32 v116, 16, v117
	v_and_b32_e32 v117, 0xffff0000, v117
	v_lshl_add_u64 v[112:113], v[164:165], 0, v[112:113]
	v_cndmask_b32_e32 v118, v208, v206, vcc
	s_waitcnt lgkmcnt(1)
; #define LAS __attribute__((address_space(3)))
;     __device__ __forceinline__ void operator()(const f32x4 (&acc)[2][2][4][2], const pg8::Unit& u, int wr, int wc, int fr, int fq) const {
;     ...
;             for (int m = 0; m < 4; ++m) {
;                 const size_t ro = (size_t)(128 * ai + 64 * wr + 16 * m + rr) * DM + cb;
; #pragma unroll
;                 for (int bj = 0; bj < 2; ++bj) {
;                     *(LAS f32x4*)(T + woff0) = acc[ai][bj][m][0]; *(LAS f32x4*)(T + woff1) = acc[ai][bj][m][1];
;                     const f32x4 a0 = *(const LAS f32x4*)(T + roff), a1 = *(const LAS f32x4*)(T + roff + 1024);
;                     const v4u t0 = xv[m][bj][0], t1 = xv[m][bj][1];
;                     const unsigned u0 = (p & 1) ? t0.z : t0.x, u1 = (p & 1) ? t0.w : t0.y, u2 = (p & 1) ? t1.z : t1.x, u3 = (p & 1) ? t1.w : t1.y;
;                     *(f32x4*)(ob + ro + 128 * bj) = (f32x4){bflo(u0), bfhi(u0), bflo(u1), bfhi(u1)} + a0; *(f32x4*)(ob + ro + 8 * DM + 128 * bj) = (f32x4){bflo(u2), bfhi(u2), bflo(u3), bfhi(u3)} + a1;
	v_pk_add_f32 v[104:105], v[104:105], v[114:115]
	v_pk_add_f32 v[106:107], v[106:107], v[116:117]
	v_cndmask_b32_e32 v119, v209, v207, vcc
	global_store_dwordx4 v[112:113], v[104:107], off nt
	s_nop 1
	v_lshlrev_b32_e32 v104, 16, v118
	v_and_b32_e32 v105, 0xffff0000, v118
	v_lshlrev_b32_e32 v106, 16, v119
	v_and_b32_e32 v107, 0xffff0000, v119
	s_waitcnt lgkmcnt(0)
	v_pk_add_f32 v[104:105], v[108:109], v[104:105]
	v_add_co_u32_e64 v108, s[4:5], s47, v112
	v_pk_add_f32 v[106:107], v[110:111], v[106:107]
	s_nop 0
	v_addc_co_u32_e64 v109, s[4:5], 0, v113, s[4:5]
	global_store_dwordx4 v[108:109], v[104:107], off nt
	ds_write_b128 v179, v[100:103]
	ds_write_b128 v180, v[96:99]
	ds_read_b128 v[96:99], v178
	ds_read_b128 v[100:103], v178 offset:1024
	v_cndmask_b32_e32 v105, v204, v202, vcc
	v_cndmask_b32_e32 v107, v205, v203, vcc
	v_lshlrev_b32_e32 v104, 16, v105
	v_and_b32_e32 v105, 0xffff0000, v105
	v_lshlrev_b32_e32 v106, 16, v107
	v_and_b32_e32 v107, 0xffff0000, v107
	v_cndmask_b32_e32 v110, v212, v210, vcc
	v_cndmask_b32_e32 v111, v213, v211, vcc
	s_waitcnt lgkmcnt(1)
	v_pk_add_f32 v[96:97], v[96:97], v[104:105]
	v_pk_add_f32 v[98:99], v[98:99], v[106:107]
	global_store_dwordx4 v[112:113], v[96:99], off offset:512 nt
	s_nop 1
	v_lshlrev_b32_e32 v96, 16, v110
	v_and_b32_e32 v97, 0xffff0000, v110
	v_lshlrev_b32_e32 v98, 16, v111
	v_and_b32_e32 v99, 0xffff0000, v111
	s_waitcnt lgkmcnt(0)
	v_pk_add_f32 v[96:97], v[100:101], v[96:97]
	v_pk_add_f32 v[98:99], v[102:103], v[98:99]
	global_store_dwordx4 v[108:109], v[96:99], off offset:512 nt
	ds_write_b128 v179, v[92:95]
	ds_write_b128 v180, v[88:91]
	ds_read_b128 v[88:91], v178
	ds_read_b128 v[92:95], v178 offset:1024
	v_cndmask_b32_e32 v99, v216, v214, vcc
	v_cndmask_b32_e32 v101, v217, v215, vcc
	v_lshlrev_b64 v[96:97], 12, v[224:225]
	v_lshlrev_b32_e32 v98, 16, v99
	v_and_b32_e32 v99, 0xffff0000, v99
	v_lshlrev_b32_e32 v100, 16, v101
	v_and_b32_e32 v101, 0xffff0000, v101
	v_lshl_add_u64 v[96:97], v[164:165], 0, v[96:97]
	v_cndmask_b32_e32 v102, v220, v218, vcc
	s_waitcnt lgkmcnt(1)
	v_pk_add_f32 v[88:89], v[88:89], v[98:99]
	v_pk_add_f32 v[90:91], v[90:91], v[100:101]
	v_cndmask_b32_e32 v103, v221, v219, vcc
	global_store_dwordx4 v[96:97], v[88:91], off nt
	s_nop 1
	v_lshlrev_b32_e32 v88, 16, v102
	v_and_b32_e32 v89, 0xffff0000, v102
	v_lshlrev_b32_e32 v90, 16, v103
	v_and_b32_e32 v91, 0xffff0000, v103
	s_waitcnt lgkmcnt(0)
	v_pk_add_f32 v[88:89], v[92:93], v[88:89]
	v_add_co_u32_e64 v92, s[4:5], s47, v96
	v_pk_add_f32 v[90:91], v[94:95], v[90:91]
	s_nop 0
	v_addc_co_u32_e64 v93, s[4:5], 0, v97, s[4:5]
	global_store_dwordx4 v[92:93], v[88:91], off nt
	ds_write_b128 v179, v[84:87]
	ds_write_b128 v180, v[80:83]
	ds_read_b128 v[80:83], v178
	ds_read_b128 v[84:87], v178 offset:1024
	v_cndmask_b32_e32 v89, v146, v144, vcc
	v_cndmask_b32_e32 v91, v147, v145, vcc
	v_lshlrev_b32_e32 v88, 16, v89
	v_and_b32_e32 v89, 0xffff0000, v89
	v_lshlrev_b32_e32 v90, 16, v91
	v_and_b32_e32 v91, 0xffff0000, v91
	v_cndmask_b32_e32 v94, v150, v148, vcc
	v_cndmask_b32_e32 v95, v151, v149, vcc
	s_waitcnt lgkmcnt(1)
	v_pk_add_f32 v[80:81], v[80:81], v[88:89]
	v_pk_add_f32 v[82:83], v[82:83], v[90:91]
	global_store_dwordx4 v[96:97], v[80:83], off offset:512 nt
	s_nop 1
	v_lshlrev_b32_e32 v80, 16, v94
	v_and_b32_e32 v81, 0xffff0000, v94
	v_lshlrev_b32_e32 v82, 16, v95
	v_and_b32_e32 v83, 0xffff0000, v95
	s_waitcnt lgkmcnt(0)
	v_pk_add_f32 v[80:81], v[84:85], v[80:81]
	v_pk_add_f32 v[82:83], v[86:87], v[82:83]
	global_store_dwordx4 v[92:93], v[80:83], off offset:512 nt
	ds_write_b128 v179, v[76:79]
	ds_write_b128 v180, v[72:75]
	ds_read_b128 v[72:75], v178
	ds_read_b128 v[76:79], v178 offset:1024
	v_cndmask_b32_e32 v83, v138, v136, vcc
	v_cndmask_b32_e32 v85, v139, v137, vcc
	v_lshlrev_b64 v[80:81], 12, v[170:171]
	v_lshlrev_b32_e32 v82, 16, v83
	v_and_b32_e32 v83, 0xffff0000, v83
	v_lshlrev_b32_e32 v84, 16, v85
	v_and_b32_e32 v85, 0xffff0000, v85
	v_lshl_add_u64 v[80:81], v[164:165], 0, v[80:81]
	v_cndmask_b32_e32 v86, v142, v140, vcc
	s_waitcnt lgkmcnt(1)
	v_pk_add_f32 v[72:73], v[72:73], v[82:83]
	v_pk_add_f32 v[74:75], v[74:75], v[84:85]
	v_cndmask_b32_e32 v87, v143, v141, vcc
	global_store_dwordx4 v[80:81], v[72:75], off nt
	s_nop 1
	v_lshlrev_b32_e32 v72, 16, v86
	v_and_b32_e32 v73, 0xffff0000, v86
	v_lshlrev_b32_e32 v74, 16, v87
	v_and_b32_e32 v75, 0xffff0000, v87
	s_waitcnt lgkmcnt(0)
	v_pk_add_f32 v[72:73], v[76:77], v[72:73]
	v_add_co_u32_e64 v76, s[4:5], s47, v80
	v_pk_add_f32 v[74:75], v[78:79], v[74:75]
	s_nop 0
	v_addc_co_u32_e64 v77, s[4:5], 0, v81, s[4:5]
	global_store_dwordx4 v[76:77], v[72:75], off nt
	ds_write_b128 v179, v[68:71]
	ds_write_b128 v180, v[64:67]
	ds_read_b128 v[64:67], v178
	ds_read_b128 v[68:71], v178 offset:1024
	v_cndmask_b32_e32 v73, v130, v128, vcc
	v_cndmask_b32_e32 v75, v131, v129, vcc
	v_lshlrev_b32_e32 v72, 16, v73
	v_and_b32_e32 v73, 0xffff0000, v73
	v_lshlrev_b32_e32 v74, 16, v75
	v_and_b32_e32 v75, 0xffff0000, v75
	v_cndmask_b32_e32 v78, v134, v132, vcc
	v_cndmask_b32_e32 v79, v135, v133, vcc
	s_waitcnt lgkmcnt(1)
	v_pk_add_f32 v[64:65], v[64:65], v[72:73]
	v_pk_add_f32 v[66:67], v[66:67], v[74:75]
	global_store_dwordx4 v[80:81], v[64:67], off offset:512 nt
	v_add_u32_e32 v130, 0x80, v166
	v_ashrrev_i32_e32 v131, 31, v130
	v_lshlrev_b32_e32 v64, 16, v78
	v_and_b32_e32 v65, 0xffff0000, v78
	v_lshlrev_b32_e32 v66, 16, v79
	v_and_b32_e32 v67, 0xffff0000, v79
	s_waitcnt lgkmcnt(0)
; #define LAS __attribute__((address_space(3)))
; #define NTLD(p) __builtin_nontemporal_load(p)
;     __device__ __forceinline__ void operator()(const f32x4 (&acc)[2][2][4][2], const pg8::Unit& u, int wr, int wc, int fr, int fq) const {
;     ...
;         for (int ai = 0; ai < 2; ++ai) {
;             v4u xv[4][2][2];
; #pragma unroll
;             for (int m = 0; m < 4; ++m) {
;                 const size_t ro = (size_t)(128 * ai + 64 * wr + 16 * m + rr) * DM + (cb & ~7);
; #pragma unroll
;                 for (int bj = 0; bj < 2; ++bj) { xv[m][bj][0] = NTLD((const v4u*)(xb + ro + 128 * bj)); xv[m][bj][1] = NTLD((const v4u*)(xb + ro + 8 * DM + 128 * bj)); }
;             }
; #pragma unroll
;             for (int m = 0; m < 4; ++m) {
;                 const size_t ro = (size_t)(128 * ai + 64 * wr + 16 * m + rr) * DM + cb;
; #pragma unroll
;                 for (int bj = 0; bj < 2; ++bj) {
;                     *(LAS f32x4*)(T + woff0) = acc[ai][bj][m][0]; *(LAS f32x4*)(T + woff1) = acc[ai][bj][m][1];
;                     const f32x4 a0 = *(const LAS f32x4*)(T + roff), a1 = *(const LAS f32x4*)(T + roff + 1024);
;                     const v4u t0 = xv[m][bj][0], t1 = xv[m][bj][1];
;                     const unsigned u0 = (p & 1) ? t0.z : t0.x, u1 = (p & 1) ? t0.w : t0.y, u2 = (p & 1) ? t1.z : t1.x, u3 = (p & 1) ? t1.w : t1.y;
;                     *(f32x4*)(ob + ro + 128 * bj) = (f32x4){bflo(u0), bfhi(u0), bflo(u1), bfhi(u1)} + a0; *(f32x4*)(ob + ro + 8 * DM + 128 * bj) = (f32x4){bflo(u2), bfhi(u2), bflo(u3), bfhi(u3)} + a1;
	v_pk_add_f32 v[64:65], v[68:69], v[64:65]
	v_pk_add_f32 v[66:67], v[70:71], v[66:67]
	global_store_dwordx4 v[76:77], v[64:67], off offset:512 nt
	v_add_u32_e32 v132, 0x90, v166
	v_ashrrev_i32_e32 v133, 31, v132
	v_lshlrev_b64 v[64:65], 11, v[130:131]
	v_lshl_add_u64 v[64:65], v[168:169], 0, v[64:65]
	global_load_dwordx4 v[82:85], v[64:65], off nt
	v_add_co_u32_e64 v66, s[4:5], s40, v64
	v_add_u32_e32 v134, 0xa0, v166
	s_nop 0
	v_addc_co_u32_e64 v67, s[4:5], 0, v65, s[4:5]
	global_load_dwordx4 v[86:89], v[66:67], off nt
	global_load_dwordx4 v[90:93], v[64:65], off offset:256 nt
	global_load_dwordx4 v[94:97], v[66:67], off offset:256 nt
	v_lshlrev_b64 v[64:65], 11, v[132:133]
	v_lshl_add_u64 v[64:65], v[168:169], 0, v[64:65]
	v_add_co_u32_e64 v66, s[4:5], s40, v64
	v_ashrrev_i32_e32 v135, 31, v134
	s_nop 0
	v_addc_co_u32_e64 v67, s[4:5], 0, v65, s[4:5]
	global_load_dwordx4 v[98:101], v[64:65], off nt
	global_load_dwordx4 v[102:105], v[64:65], off offset:256 nt
	global_load_dwordx4 v[106:109], v[66:67], off nt
	global_load_dwordx4 v[110:113], v[66:67], off offset:256 nt
	v_lshlrev_b64 v[64:65], 11, v[134:135]
	v_lshl_add_u64 v[64:65], v[168:169], 0, v[64:65]
	v_add_co_u32_e64 v66, s[4:5], s40, v64
	v_add_u32_e32 v80, 0xb0, v166
	s_nop 0
	v_addc_co_u32_e64 v67, s[4:5], 0, v65, s[4:5]
	global_load_dwordx4 v[114:117], v[64:65], off nt
	global_load_dwordx4 v[118:121], v[64:65], off offset:256 nt
	global_load_dwordx4 v[122:125], v[66:67], off nt
	global_load_dwordx4 v[126:129], v[66:67], off offset:256 nt
	v_ashrrev_i32_e32 v81, 31, v80
	v_lshlrev_b64 v[64:65], 11, v[80:81]
	v_lshl_add_u64 v[64:65], v[168:169], 0, v[64:65]
	v_add_co_u32_e64 v68, s[4:5], s40, v64
	v_lshlrev_b64 v[130:131], 12, v[130:131]
	s_nop 0
	v_addc_co_u32_e64 v69, s[4:5], 0, v65, s[4:5]
	global_load_dwordx4 v[72:75], v[64:65], off nt
	s_nop 0
	global_load_dwordx4 v[64:67], v[64:65], off offset:256 nt
	s_nop 0
	global_load_dwordx4 v[76:79], v[68:69], off nt
	s_nop 0
	global_load_dwordx4 v[68:71], v[68:69], off offset:256 nt
	ds_write_b128 v179, v[60:63]
	ds_write_b128 v180, v[56:59]
	ds_read_b128 v[56:59], v178
	ds_read_b128 v[60:63], v178 offset:1024
	v_lshl_add_u64 v[130:131], v[164:165], 0, v[130:131]
	s_waitcnt vmcnt(15)
	v_cndmask_b32_e32 v84, v84, v82, vcc
	v_cndmask_b32_e32 v85, v85, v83, vcc
	v_lshlrev_b32_e32 v82, 16, v84
	v_and_b32_e32 v83, 0xffff0000, v84
	v_lshlrev_b32_e32 v84, 16, v85
	v_and_b32_e32 v85, 0xffff0000, v85
	s_waitcnt vmcnt(14)
	v_cndmask_b32_e32 v86, v88, v86, vcc
	s_waitcnt lgkmcnt(1)
	v_pk_add_f32 v[56:57], v[56:57], v[82:83]
	v_pk_add_f32 v[58:59], v[58:59], v[84:85]
	v_cndmask_b32_e32 v87, v89, v87, vcc
	global_store_dwordx4 v[130:131], v[56:59], off nt
	s_nop 1
	v_lshlrev_b32_e32 v56, 16, v86
	v_and_b32_e32 v57, 0xffff0000, v86
	v_lshlrev_b32_e32 v58, 16, v87
	v_and_b32_e32 v59, 0xffff0000, v87
	s_waitcnt lgkmcnt(0)
	v_pk_add_f32 v[56:57], v[60:61], v[56:57]
	v_add_co_u32_e64 v60, s[4:5], s47, v130
	v_pk_add_f32 v[58:59], v[62:63], v[58:59]
	s_nop 0
	v_addc_co_u32_e64 v61, s[4:5], 0, v131, s[4:5]
	global_store_dwordx4 v[60:61], v[56:59], off nt
	ds_write_b128 v179, v[52:55]
	ds_write_b128 v180, v[48:51]
	ds_read_b128 v[48:51], v178
	ds_read_b128 v[52:55], v178 offset:1024
	s_waitcnt vmcnt(15)
	v_cndmask_b32_e32 v57, v92, v90, vcc
	v_cndmask_b32_e32 v59, v93, v91, vcc
	v_lshlrev_b32_e32 v56, 16, v57
	v_and_b32_e32 v57, 0xffff0000, v57
	v_lshlrev_b32_e32 v58, 16, v59
	v_and_b32_e32 v59, 0xffff0000, v59
	s_waitcnt vmcnt(14)
	v_cndmask_b32_e32 v62, v96, v94, vcc
	v_cndmask_b32_e32 v63, v97, v95, vcc
	s_waitcnt lgkmcnt(1)
	v_pk_add_f32 v[48:49], v[48:49], v[56:57]
	v_pk_add_f32 v[50:51], v[50:51], v[58:59]
	global_store_dwordx4 v[130:131], v[48:51], off offset:512 nt
	s_nop 1
	v_lshlrev_b32_e32 v48, 16, v62
	v_and_b32_e32 v49, 0xffff0000, v62
	v_lshlrev_b32_e32 v50, 16, v63
	v_and_b32_e32 v51, 0xffff0000, v63
	s_waitcnt lgkmcnt(0)
	v_pk_add_f32 v[48:49], v[52:53], v[48:49]
	v_pk_add_f32 v[50:51], v[54:55], v[50:51]
	global_store_dwordx4 v[60:61], v[48:51], off offset:512 nt
	ds_write_b128 v179, v[44:47]
	ds_write_b128 v180, v[40:43]
	ds_read_b128 v[40:43], v178
	ds_read_b128 v[44:47], v178 offset:1024
	s_waitcnt vmcnt(15)
	v_cndmask_b32_e32 v51, v100, v98, vcc
	v_cndmask_b32_e32 v53, v101, v99, vcc
	v_lshlrev_b64 v[48:49], 12, v[132:133]
	v_lshlrev_b32_e32 v50, 16, v51
	v_and_b32_e32 v51, 0xffff0000, v51
	v_lshlrev_b32_e32 v52, 16, v53
	v_and_b32_e32 v53, 0xffff0000, v53
	v_lshl_add_u64 v[48:49], v[164:165], 0, v[48:49]
	s_waitcnt vmcnt(13)
	v_cndmask_b32_e32 v54, v108, v106, vcc
	s_waitcnt lgkmcnt(1)
	v_pk_add_f32 v[40:41], v[40:41], v[50:51]
	v_pk_add_f32 v[42:43], v[42:43], v[52:53]
	v_cndmask_b32_e32 v55, v109, v107, vcc
	global_store_dwordx4 v[48:49], v[40:43], off nt
	s_nop 1
	v_lshlrev_b32_e32 v40, 16, v54
	v_and_b32_e32 v41, 0xffff0000, v54
	v_lshlrev_b32_e32 v42, 16, v55
	v_and_b32_e32 v43, 0xffff0000, v55
	s_waitcnt lgkmcnt(0)
; #define PG8_BAR __builtin_amdgcn_s_barrier()
; #define LAS __attribute__((address_space(3)))
; template <class Epi, class Sched, bool ALIGN_EPI = false, bool SP2 = false>
; __device__ __forceinline__ void gemm_phase(PG8_LAS unsigned char* lds, const Gemm g, const Sched& S, const Epi& E) {
;     ...
;         if constexpr (ALIGN_EPI) { if (wr == 0) PG8_BAR; }
;         if constexpr (!Epi::AFTER_DRAIN) { E(acc, cur, wr, wc, fr, fq); S.done(cur); }
;         if (!has_next) break;
; #pragma unroll
;         for (int a = 0; a < 2; ++a)
; #pragma unroll
;             for (int b = 0; b < 2; ++b)
; #pragma unroll
;                 for (int m = 0; m < 4; ++m)
; #pragma unroll
;                     for (int n = 0; n < 2; ++n) acc[a][b][m][n] = (f32x4){0.f, 0.f, 0.f, 0.f};
;         cur = nxt; cA = nA; cB = nB; ++ui;
;         if constexpr (ALIGN_EPI) { if (wr == 1) PG8_BAR; }
;     }
;     __device__ __forceinline__ void operator()(const f32x4 (&acc)[2][2][4][2], const pg8::Unit& u, int wr, int wc, int fr, int fq) const {
;     ...
;             for (int m = 0; m < 4; ++m) {
;                 const size_t ro = (size_t)(128 * ai + 64 * wr + 16 * m + rr) * DM + cb;
; #pragma unroll
;                 for (int bj = 0; bj < 2; ++bj) {
;                     *(LAS f32x4*)(T + woff0) = acc[ai][bj][m][0]; *(LAS f32x4*)(T + woff1) = acc[ai][bj][m][1];
;                     const f32x4 a0 = *(const LAS f32x4*)(T + roff), a1 = *(const LAS f32x4*)(T + roff + 1024);
;                     const v4u t0 = xv[m][bj][0], t1 = xv[m][bj][1];
;                     const unsigned u0 = (p & 1) ? t0.z : t0.x, u1 = (p & 1) ? t0.w : t0.y, u2 = (p & 1) ? t1.z : t1.x, u3 = (p & 1) ? t1.w : t1.y;
;                     *(f32x4*)(ob + ro + 128 * bj) = (f32x4){bflo(u0), bfhi(u0), bflo(u1), bfhi(u1)} + a0; *(f32x4*)(ob + ro + 8 * DM + 128 * bj) = (f32x4){bflo(u2), bfhi(u2), bflo(u3), bfhi(u3)} + a1;
	v_pk_add_f32 v[40:41], v[44:45], v[40:41]
	v_add_co_u32_e64 v44, s[4:5], s47, v48
	v_pk_add_f32 v[42:43], v[46:47], v[42:43]
	s_nop 0
	v_addc_co_u32_e64 v45, s[4:5], 0, v49, s[4:5]
	global_store_dwordx4 v[44:45], v[40:43], off nt
	ds_write_b128 v179, v[36:39]
	ds_write_b128 v180, v[32:35]
	ds_read_b128 v[32:35], v178
	ds_read_b128 v[36:39], v178 offset:1024
	v_cndmask_b32_e32 v41, v104, v102, vcc
	v_cndmask_b32_e32 v43, v105, v103, vcc
	v_lshlrev_b32_e32 v40, 16, v41
	v_and_b32_e32 v41, 0xffff0000, v41
	v_lshlrev_b32_e32 v42, 16, v43
	v_and_b32_e32 v43, 0xffff0000, v43
	s_waitcnt vmcnt(14)
	v_cndmask_b32_e32 v46, v112, v110, vcc
	v_cndmask_b32_e32 v47, v113, v111, vcc
	s_waitcnt lgkmcnt(1)
	v_pk_add_f32 v[32:33], v[32:33], v[40:41]
	v_pk_add_f32 v[34:35], v[34:35], v[42:43]
	global_store_dwordx4 v[48:49], v[32:35], off offset:512 nt
	s_nop 1
	v_lshlrev_b32_e32 v32, 16, v46
	v_and_b32_e32 v33, 0xffff0000, v46
	v_lshlrev_b32_e32 v34, 16, v47
	v_and_b32_e32 v35, 0xffff0000, v47
	s_waitcnt lgkmcnt(0)
	v_pk_add_f32 v[32:33], v[36:37], v[32:33]
	v_pk_add_f32 v[34:35], v[38:39], v[34:35]
	global_store_dwordx4 v[44:45], v[32:35], off offset:512 nt
	ds_write_b128 v179, v[28:31]
	ds_write_b128 v180, v[24:27]
	ds_read_b128 v[24:27], v178
	ds_read_b128 v[28:31], v178 offset:1024
	s_waitcnt vmcnt(15)
	v_cndmask_b32_e32 v35, v116, v114, vcc
	v_cndmask_b32_e32 v37, v117, v115, vcc
	v_lshlrev_b64 v[32:33], 12, v[134:135]
	v_lshlrev_b32_e32 v34, 16, v35
	v_and_b32_e32 v35, 0xffff0000, v35
	v_lshlrev_b32_e32 v36, 16, v37
	v_and_b32_e32 v37, 0xffff0000, v37
	v_lshl_add_u64 v[32:33], v[164:165], 0, v[32:33]
	s_waitcnt vmcnt(13)
	v_cndmask_b32_e32 v38, v124, v122, vcc
	s_waitcnt lgkmcnt(1)
	v_pk_add_f32 v[24:25], v[24:25], v[34:35]
	v_pk_add_f32 v[26:27], v[26:27], v[36:37]
	v_cndmask_b32_e32 v39, v125, v123, vcc
	global_store_dwordx4 v[32:33], v[24:27], off nt
	s_nop 1
	v_lshlrev_b32_e32 v24, 16, v38
	v_and_b32_e32 v25, 0xffff0000, v38
	v_lshlrev_b32_e32 v26, 16, v39
	v_and_b32_e32 v27, 0xffff0000, v39
	s_waitcnt lgkmcnt(0)
	v_pk_add_f32 v[24:25], v[28:29], v[24:25]
	v_add_co_u32_e64 v28, s[4:5], s47, v32
	v_pk_add_f32 v[26:27], v[30:31], v[26:27]
	s_nop 0
	v_addc_co_u32_e64 v29, s[4:5], 0, v33, s[4:5]
	global_store_dwordx4 v[28:29], v[24:27], off nt
	ds_write_b128 v179, v[20:23]
	ds_write_b128 v180, v[16:19]
	ds_read_b128 v[16:19], v178
	ds_read_b128 v[20:23], v178 offset:1024
	v_cndmask_b32_e32 v25, v120, v118, vcc
	v_cndmask_b32_e32 v27, v121, v119, vcc
	v_lshlrev_b32_e32 v24, 16, v25
	v_and_b32_e32 v25, 0xffff0000, v25
	v_lshlrev_b32_e32 v26, 16, v27
	v_and_b32_e32 v27, 0xffff0000, v27
	s_waitcnt vmcnt(14)
	v_cndmask_b32_e32 v30, v128, v126, vcc
	v_cndmask_b32_e32 v31, v129, v127, vcc
	s_waitcnt lgkmcnt(1)
	v_pk_add_f32 v[16:17], v[16:17], v[24:25]
	v_pk_add_f32 v[18:19], v[18:19], v[26:27]
	global_store_dwordx4 v[32:33], v[16:19], off offset:512 nt
	s_nop 1
	v_lshlrev_b32_e32 v16, 16, v30
	v_and_b32_e32 v17, 0xffff0000, v30
	v_lshlrev_b32_e32 v18, 16, v31
	v_and_b32_e32 v19, 0xffff0000, v31
	s_waitcnt lgkmcnt(0)
	v_pk_add_f32 v[16:17], v[20:21], v[16:17]
	v_pk_add_f32 v[18:19], v[22:23], v[18:19]
	global_store_dwordx4 v[28:29], v[16:19], off offset:512 nt
	ds_write_b128 v179, v[12:15]
	ds_write_b128 v180, v[8:11]
	ds_read_b128 v[8:11], v178
	ds_read_b128 v[12:15], v178 offset:1024
	s_waitcnt vmcnt(15)
	v_cndmask_b32_e32 v19, v74, v72, vcc
	v_cndmask_b32_e32 v21, v75, v73, vcc
	v_lshlrev_b64 v[16:17], 12, v[80:81]
	v_lshlrev_b32_e32 v18, 16, v19
	v_and_b32_e32 v19, 0xffff0000, v19
	v_lshlrev_b32_e32 v20, 16, v21
	v_and_b32_e32 v21, 0xffff0000, v21
	v_lshl_add_u64 v[16:17], v[164:165], 0, v[16:17]
	s_waitcnt vmcnt(13)
	v_cndmask_b32_e32 v22, v78, v76, vcc
	s_waitcnt lgkmcnt(1)
	v_pk_add_f32 v[8:9], v[8:9], v[18:19]
	v_pk_add_f32 v[10:11], v[10:11], v[20:21]
	v_cndmask_b32_e32 v23, v79, v77, vcc
	global_store_dwordx4 v[16:17], v[8:11], off nt
	s_nop 1
	v_lshlrev_b32_e32 v8, 16, v22
	v_and_b32_e32 v9, 0xffff0000, v22
	v_lshlrev_b32_e32 v10, 16, v23
	v_and_b32_e32 v11, 0xffff0000, v23
	s_waitcnt lgkmcnt(0)
	v_pk_add_f32 v[8:9], v[12:13], v[8:9]
	v_add_co_u32_e64 v12, s[4:5], s47, v16
	v_pk_add_f32 v[10:11], v[14:15], v[10:11]
	s_nop 0
	v_addc_co_u32_e64 v13, s[4:5], 0, v17, s[4:5]
	global_store_dwordx4 v[12:13], v[8:11], off nt
	ds_write_b128 v179, v[4:7]
	ds_write_b128 v180, v[0:3]
	ds_read_b128 v[0:3], v178
	ds_read_b128 v[4:7], v178 offset:1024
	v_cndmask_b32_e32 v9, v66, v64, vcc
	v_cndmask_b32_e32 v11, v67, v65, vcc
	v_lshlrev_b32_e32 v8, 16, v9
	v_and_b32_e32 v9, 0xffff0000, v9
	v_lshlrev_b32_e32 v10, 16, v11
	v_and_b32_e32 v11, 0xffff0000, v11
	s_waitcnt vmcnt(14)
	v_cndmask_b32_e32 v14, v70, v68, vcc
	v_cndmask_b32_e32 v15, v71, v69, vcc
	s_waitcnt lgkmcnt(1)
	v_pk_add_f32 v[0:1], v[0:1], v[8:9]
	v_pk_add_f32 v[2:3], v[2:3], v[10:11]
	global_store_dwordx4 v[16:17], v[0:3], off offset:512 nt
	s_andn2_b64 vcc, exec, s[0:1]
	s_mov_b64 s[0:1], -1
	v_lshlrev_b32_e32 v0, 16, v14
	v_and_b32_e32 v1, 0xffff0000, v14
	v_lshlrev_b32_e32 v2, 16, v15
	v_and_b32_e32 v3, 0xffff0000, v15
	s_waitcnt lgkmcnt(0)
	v_pk_add_f32 v[0:1], v[4:5], v[0:1]
	v_pk_add_f32 v[2:3], v[6:7], v[2:3]
	global_store_dwordx4 v[12:13], v[0:3], off offset:512 nt
	s_cbranch_vccnz .LBB0_1228
	s_andn2_b64 vcc, exec, s[8:9]
	s_cbranch_vccnz .LBB0_1227
	s_barrier
	s_branch .LBB0_1227
